# v20 + non-temporal hint on the read-once memory-token normalisation loads of the prologue
# baseline (speedup 1.0000x reference)
; __device__ __forceinline__ unsigned pk2(float lo, float hi) { return f2bf(lo) | (f2bf(hi) << 16); }
; __global__ void __launch_bounds__(512, 2) fwd_kernel(Args args) {
;     ...
;             for (int m = gw; m < MEM; m += NGW) {
;                 const f32x4* xr = (const f32x4*)(mem + (size_t)m * D) + lane; f32x4 v[4]; float s = 0.f;
; #pragma unroll
;                 for (int j = 0; j < 4; ++j) { v[j] = xr[64 * j]; s += (v[j][0] * v[j][0] + v[j][1] * v[j][1]) + (v[j][2] * v[j][2] + v[j][3] * v[j][3]); }
;                 s = wave_sum(s); const float rs = rsqrtf(s * (1.0f / 1024.0f) + 1e-6f);
; #pragma unroll
;                 for (int l = 0; l < 2; ++l) { unsigned long long* o8 = (unsigned long long*)(MN + ((size_t)l * MEM + m) * D) + lane;
; #pragma unroll
;                     for (int j = 0; j < 4; ++j) { const f32x4 gg = ((const f32x4*)(g_mem + l * 1024) + lane)[64 * j];
;                         o8[64 * j] = (unsigned long long)pk2(v[j][0] * rs * gg[0], v[j][1] * rs * gg[1]) | ((unsigned long long)pk2(v[j][2] * rs * gg[2], v[j][3] * rs * gg[3]) << 32); } }
.LBB0_622:
	global_load_dwordx4 v[34:37], v[16:17], off offset:-3072 nt
	global_load_dwordx4 v[38:41], v[16:17], off offset:-2048 nt
	global_load_dwordx4 v[42:45], v[16:17], off nt
	global_load_dwordx4 v[46:49], v[16:17], off offset:-1024 nt
	global_load_dwordx4 v[50:53], v[4:5], off nt
	v_add_co_u32_e32 v20, vcc, s9, v14
	s_add_i32 s8, s8, s38
	s_nop 0
	v_addc_co_u32_e32 v21, vcc, -1, v15, vcc
	v_add_co_u32_e32 v28, vcc, s11, v14
	v_lshl_add_u64 v[16:17], v[16:17], 0, s[14:15]
	s_nop 0
	v_addc_co_u32_e32 v29, vcc, -1, v15, vcc
	s_cmpk_gt_i32 s8, 0xff
	s_waitcnt vmcnt(4)
	v_pk_mul_f32 v[54:55], v[36:37], v[36:37]
	v_pk_mul_f32 v[56:57], v[34:35], v[34:35]
	s_waitcnt vmcnt(3)
	v_pk_mul_f32 v[58:59], v[40:41], v[40:41]
	v_pk_mul_f32 v[60:61], v[38:39], v[38:39]
	v_pk_mov_b32 v[66:67], v[56:57], v[54:55] op_sel:[1,0]
	v_mov_b32_e32 v57, v55
	v_pk_mov_b32 v[54:55], v[60:61], v[58:59] op_sel:[1,0]
	v_mov_b32_e32 v61, v59
	s_waitcnt vmcnt(1)
	v_mul_f32_e32 v62, v47, v47
	v_mul_f32_e32 v64, v49, v49
	v_pk_add_f32 v[56:57], v[66:67], v[56:57]
	v_pk_add_f32 v[54:55], v[54:55], v[60:61]
	v_mul_f32_e32 v19, v42, v42
	v_mul_f32_e32 v27, v43, v43
	v_mul_f32_e32 v31, v44, v44
	v_mul_f32_e32 v33, v45, v45
	v_pk_fma_f32 v[58:59], v[46:47], v[46:47], v[62:63] op_sel_hi:[1,1,0]
	v_pk_fma_f32 v[62:63], v[48:49], v[48:49], v[64:65] op_sel_hi:[1,1,0]
	v_pk_add_f32 v[56:57], v[56:57], v[56:57] op_sel:[0,1] op_sel_hi:[1,0]
	v_pk_add_f32 v[54:55], v[54:55], v[54:55] op_sel:[0,1] op_sel_hi:[1,0]
	v_mov_b32_e32 v59, v31
	v_mov_b32_e32 v63, v33
	v_mov_b32_e32 v57, v19
	v_mov_b32_e32 v55, v27
	v_pk_add_f32 v[58:59], v[58:59], v[62:63]
	v_pk_add_f32 v[54:55], v[56:57], v[54:55]
	s_nop 0
	v_pk_add_f32 v[54:55], v[54:55], v[58:59]
	s_nop 0
	v_add_f32_e32 v19, v54, v55
	ds_bpermute_b32 v27, v1, v19
	s_waitcnt lgkmcnt(0)
	v_add_f32_e32 v19, v19, v27
	ds_bpermute_b32 v27, v22, v19
	s_waitcnt lgkmcnt(0)
	v_add_f32_e32 v19, v19, v27
	ds_bpermute_b32 v27, v23, v19
	s_waitcnt lgkmcnt(0)
	v_add_f32_e32 v19, v19, v27
	ds_bpermute_b32 v27, v24, v19
	s_waitcnt lgkmcnt(0)
	v_add_f32_e32 v19, v19, v27
	ds_bpermute_b32 v27, v25, v19
	s_waitcnt lgkmcnt(0)
	v_add_f32_e32 v19, v19, v27
	ds_bpermute_b32 v27, v26, v19
	s_waitcnt lgkmcnt(0)
	v_add_f32_e32 v19, v19, v27
	v_fmamk_f32 v19, v19, 0x3a800000, v18
	v_mul_f32_e32 v27, 0x4b800000, v19
	v_cmp_gt_f32_e32 vcc, s1, v19
	s_nop 1
	v_cndmask_b32_e32 v19, v19, v27, vcc
	v_rsq_f32_e32 v19, v19
	s_nop 0
	v_mul_f32_e32 v27, 0x45800000, v19
	v_cndmask_b32_e32 v19, v19, v27, vcc
	v_mul_f32_e32 v27, v19, v34
	v_mul_f32_e32 v33, v19, v36
	v_mul_f32_e32 v31, v19, v35
	v_mul_f32_e32 v54, v19, v37
	s_waitcnt vmcnt(0)
	v_mul_f32_e32 v34, v27, v50
	v_mul_f32_e32 v36, v33, v52
	v_mul_f32_e32 v35, v31, v51
	v_mul_f32_e32 v37, v54, v53
	v_bfe_u32 v50, v34, 16, 1
	v_bfe_u32 v52, v36, 16, 1
	v_bfe_u32 v51, v35, 16, 1
	v_bfe_u32 v53, v37, 16, 1
	v_add3_u32 v34, v34, v50, s2
	v_add3_u32 v36, v36, v52, s2
	v_add3_u32 v35, v35, v51, s2
	v_add3_u32 v37, v37, v53, s2
	v_lshrrev_b32_e32 v34, 16, v34
	v_lshrrev_b32_e32 v36, 16, v36
	v_and_or_b32 v34, v35, s3, v34
	v_and_or_b32 v35, v37, s3, v36
	global_store_dwordx2 v[20:21], v[34:35], off
	global_load_dwordx4 v[34:37], v[4:5], off offset:1024 nt
	v_mul_f32_e32 v38, v19, v38
	v_mul_f32_e32 v40, v19, v40
	v_mul_f32_e32 v39, v19, v39
	v_mul_f32_e32 v41, v19, v41
	v_mul_f32_e32 v46, v19, v46
	v_mul_f32_e32 v48, v19, v48
	v_mul_f32_e32 v47, v19, v47
	v_mul_f32_e32 v49, v19, v49
	v_mul_f32_e32 v42, v19, v42
	v_mul_f32_e32 v44, v19, v44
	v_mul_f32_e32 v43, v19, v43
	v_mul_f32_e32 v19, v19, v45
	s_waitcnt vmcnt(0)
; __device__ __forceinline__ unsigned pk2(float lo, float hi) { return f2bf(lo) | (f2bf(hi) << 16); }
; __global__ void __launch_bounds__(512, 2) fwd_kernel(Args args) {
;     ...
;                 for (int l = 0; l < 2; ++l) { unsigned long long* o8 = (unsigned long long*)(MN + ((size_t)l * MEM + m) * D) + lane;
; #pragma unroll
;                     for (int j = 0; j < 4; ++j) { const f32x4 gg = ((const f32x4*)(g_mem + l * 1024) + lane)[64 * j];
;                         o8[64 * j] = (unsigned long long)pk2(v[j][0] * rs * gg[0], v[j][1] * rs * gg[1]) | ((unsigned long long)pk2(v[j][2] * rs * gg[2], v[j][3] * rs * gg[3]) << 32); } }
	v_mul_f32_e32 v20, v38, v34
	v_mul_f32_e32 v34, v40, v36
	v_mul_f32_e32 v21, v39, v35
	v_mul_f32_e32 v35, v41, v37
	v_bfe_u32 v36, v20, 16, 1
	v_bfe_u32 v50, v34, 16, 1
	v_bfe_u32 v37, v21, 16, 1
	v_bfe_u32 v51, v35, 16, 1
	v_add3_u32 v20, v20, v36, s2
	v_add3_u32 v34, v34, v50, s2
	v_add3_u32 v21, v21, v37, s2
	v_add3_u32 v35, v35, v51, s2
	v_lshrrev_b32_e32 v20, 16, v20
	v_lshrrev_b32_e32 v34, 16, v34
	v_and_or_b32 v20, v21, s3, v20
	v_and_or_b32 v21, v35, s3, v34
	global_store_dwordx2 v[28:29], v[20:21], off offset:-3584
	global_load_dwordx4 v[34:37], v[4:5], off offset:2048 nt
	s_waitcnt vmcnt(0)
	v_mul_f32_e32 v20, v46, v34
	v_mul_f32_e32 v34, v48, v36
	v_mul_f32_e32 v21, v47, v35
	v_mul_f32_e32 v35, v49, v37
	v_bfe_u32 v36, v20, 16, 1
	v_bfe_u32 v50, v34, 16, 1
	v_bfe_u32 v37, v21, 16, 1
	v_bfe_u32 v51, v35, 16, 1
	v_add3_u32 v20, v20, v36, s2
	v_add3_u32 v34, v34, v50, s2
	v_add3_u32 v21, v21, v37, s2
	v_add3_u32 v35, v35, v51, s2
	v_lshrrev_b32_e32 v20, 16, v20
	v_lshrrev_b32_e32 v34, 16, v34
	v_and_or_b32 v20, v21, s3, v20
	v_and_or_b32 v21, v35, s3, v34
	global_store_dwordx2 v[28:29], v[20:21], off offset:-3072
	global_load_dwordx4 v[34:37], v[4:5], off offset:3072 nt
	s_waitcnt vmcnt(0)
	v_mul_f32_e32 v20, v42, v34
	v_mul_f32_e32 v34, v44, v36
	v_mul_f32_e32 v21, v43, v35
	v_mul_f32_e32 v35, v19, v37
	v_bfe_u32 v36, v20, 16, 1
	v_bfe_u32 v45, v34, 16, 1
	v_bfe_u32 v37, v21, 16, 1
	v_bfe_u32 v50, v35, 16, 1
	v_add3_u32 v20, v20, v36, s2
	v_add3_u32 v34, v34, v45, s2
	v_add3_u32 v21, v21, v37, s2
	v_add3_u32 v35, v35, v50, s2
	v_lshrrev_b32_e32 v20, 16, v20
	v_lshrrev_b32_e32 v34, 16, v34
	v_and_or_b32 v20, v21, s3, v20
	v_and_or_b32 v21, v35, s3, v34
	global_store_dwordx2 v[28:29], v[20:21], off offset:-2560
	global_load_dwordx4 v[34:37], v[6:7], off nt
	s_waitcnt vmcnt(0)
	v_mul_f32_e32 v20, v27, v34
	v_mul_f32_e32 v27, v33, v36
	v_mul_f32_e32 v21, v31, v35
	v_mul_f32_e32 v28, v54, v37
	v_bfe_u32 v29, v20, 16, 1
	v_bfe_u32 v33, v27, 16, 1
	v_bfe_u32 v31, v21, 16, 1
	v_bfe_u32 v34, v28, 16, 1
	v_add3_u32 v20, v20, v29, s2
	v_add3_u32 v27, v27, v33, s2
	v_add3_u32 v21, v21, v31, s2
	v_add3_u32 v28, v28, v34, s2
	v_lshrrev_b32_e32 v20, 16, v20
	v_lshrrev_b32_e32 v27, 16, v27
	v_and_or_b32 v20, v21, s3, v20
	v_and_or_b32 v21, v28, s3, v27
	global_store_dwordx2 v[14:15], v[20:21], off
	global_load_dwordx4 v[34:37], v[8:9], off nt
	s_waitcnt vmcnt(0)
	v_mul_f32_e32 v20, v38, v34
	v_mul_f32_e32 v27, v40, v36
	v_mul_f32_e32 v21, v39, v35
	v_mul_f32_e32 v28, v41, v37
	v_bfe_u32 v29, v20, 16, 1
	v_bfe_u32 v33, v27, 16, 1
	v_bfe_u32 v31, v21, 16, 1
	v_bfe_u32 v34, v28, 16, 1
	v_add3_u32 v20, v20, v29, s2
	v_add3_u32 v27, v27, v33, s2
	v_add3_u32 v21, v21, v31, s2
	v_add3_u32 v28, v28, v34, s2
	v_lshrrev_b32_e32 v20, 16, v20
	v_lshrrev_b32_e32 v27, 16, v27
	v_and_or_b32 v20, v21, s3, v20
	v_and_or_b32 v21, v28, s3, v27
	global_store_dwordx2 v[14:15], v[20:21], off offset:512
	global_load_dwordx4 v[34:37], v[10:11], off nt
	s_waitcnt vmcnt(0)
	v_mul_f32_e32 v20, v46, v34
	v_mul_f32_e32 v27, v48, v36
	v_mul_f32_e32 v21, v47, v35
	v_mul_f32_e32 v28, v49, v37
	v_bfe_u32 v29, v20, 16, 1
	v_bfe_u32 v33, v27, 16, 1
	v_bfe_u32 v31, v21, 16, 1
	v_bfe_u32 v34, v28, 16, 1
	v_add3_u32 v20, v20, v29, s2
	v_add3_u32 v27, v27, v33, s2
	v_add3_u32 v21, v21, v31, s2
	v_add3_u32 v28, v28, v34, s2
	v_lshrrev_b32_e32 v20, 16, v20
	v_lshrrev_b32_e32 v27, 16, v27
	v_and_or_b32 v20, v21, s3, v20
	v_and_or_b32 v21, v28, s3, v27
	global_store_dwordx2 v[14:15], v[20:21], off offset:1024
	global_load_dwordx4 v[34:37], v[12:13], off nt
	s_waitcnt vmcnt(0)
	v_mul_f32_e32 v20, v42, v34
	v_mul_f32_e32 v27, v44, v36
	v_mul_f32_e32 v21, v43, v35
	v_mul_f32_e32 v19, v19, v37
	v_bfe_u32 v28, v20, 16, 1
	v_bfe_u32 v31, v27, 16, 1
	v_bfe_u32 v29, v21, 16, 1
	v_bfe_u32 v33, v19, 16, 1
	v_add3_u32 v20, v20, v28, s2
	v_add3_u32 v27, v27, v31, s2
	v_add3_u32 v21, v21, v29, s2
	v_add3_u32 v19, v19, v33, s2
	v_lshrrev_b32_e32 v20, 16, v20
	v_lshrrev_b32_e32 v27, 16, v27
	v_and_or_b32 v20, v21, s3, v20
	v_and_or_b32 v21, v19, s3, v27
	global_store_dwordx2 v[14:15], v[20:21], off offset:1536
	v_lshl_add_u64 v[14:15], v[14:15], 0, s[12:13]
	s_cbranch_scc0 .LBB0_622
